# attention main loop: per-segment priority flips replaced by one static raise for the trailing wave half (waves 4-7); stacked on stack20
# baseline (speedup 1.0000x reference)
; #define ATT_DMA(i, slot) do { if (ABL & 1) break; const long off_ = (long)ATT_TAU(i) * KVBLK * INW; \
;         glds16(ksrc + off_, (unsigned)__builtin_amdgcn_readfirstlane(kdst + (slot) * SLOTB)); glds16(vsrc + off_, (unsigned)__builtin_amdgcn_readfirstlane(vdst + (slot) * SLOTB)); } while (0)
; #define ATT_BAR() do { if (ABL & 16) asm volatile("s_waitcnt lgkmcnt(0)" ::: "memory"); else asm volatile("s_waitcnt lgkmcnt(0)\n\ts_barrier" ::: "memory"); } while (0)
; #define ATT_SB() __builtin_amdgcn_sched_barrier(0)
; #define ATT_KAUG(tau_) do { const unsigned tb_ = __float_as_uint((float)((tau_) * KVBLK)) >> 16; \
;         if (hi) { const u32x4 w_ = (u32x4){tb_ | (tb_ << 16), tb_, 0u, 0u}; kaug0 = __builtin_bit_cast(bf16x8, w_); kaug1 = kaug0; } } while (0)
;     ...
;       { const int tn_ = ATT_TAU(1); ATT_QAUG(ATT_SIDE(tn_)); ATT_KAUG(tn_); }
;       ATT_SB(); ATT_BAR(); ATT_SB(); }
;     if (SKIP_T > 0) {
;         float qa2 = 0.f, qb2 = 0.f, da = 3.0e38f, db = 3.0e38f;
;         { const float* wall = (const float*)(shm + LDS_WS);
; #pragma unroll
;           for (int w = 0; w < NW; ++w) { qa2 = fmaxf(qa2, wall[w * 128 + 0]); qb2 = fmaxf(qb2, wall[w * 128 + 1]); da = fminf(da, wall[w * 128 + 2]); db = fminf(db, wall[w * 128 + 3]); } }
;         const int kt0 = lane * KVBLK; const int dmin = kt0 + KVBLK - 1 < q0 ? q0 - (kt0 + KVBLK - 1) : (kt0 > q0 + QB - 1 ? kt0 - (q0 + QB - 1) : 0);
;         const float pen = sl * (float)dmin - (float)SKIP_T;
;         const bool needed = dmin == 0 || !(sqrtf(qa2 * ka2) * 1.01f - pen <= da) || !(sqrtf(qb2 * kb2) * 1.01f - pen <= db);
;         const unsigned long long mask = __ballot(needed);
;         const int tR = 63 - __clzll((long long)mask), tL = __ffsll((long long)mask) - 1;
;         nR = __builtin_amdgcn_readfirstlane(tR + 1 - d0t); NTe = __builtin_amdgcn_readfirstlane(tR - tL + 1);
;         ATT_BAR();
;     }
;     if (grp == 1) { ATT_BAR(); }
;     for (int i = 1; i < NTe; ++i) {
;         const int tau = ATT_TAU(i), slot = i & 3;
;         { const int id_ = i + 2 < NTe ? i + 2 : NTe - 1; ATT_DMA(id_, (i + 2) & 3); }
;         { const lds_cptr vp = vp0 + ((i - 1) & 3) * SLOTB, kp = kp0 + slot * SLOTB;
.LBB0_334:
	v_lshlrev_b32_e32 v0, 5, v93
	v_and_b32_e32 v0, 32, v0
	v_or_b32_e32 v1, v172, v97
	v_add_u32_e32 v0, 0, v0
	v_lshlrev_b32_e32 v1, 6, v1
	v_mov_b32_e32 v15, 0
	v_add3_u32 v191, v0, v104, v1
	s_andn2_b64 vcc, exec, s[36:37]
	v_lshl_add_u32 v190, v170, 2, s20
	v_lshl_add_u32 v185, v172, 2, s20
	v_mov_b32_e32 v14, v15
	v_mov_b32_e32 v13, v15
	v_mov_b32_e32 v12, v15
	v_mov_b32_e32 v11, v15
	v_mov_b32_e32 v10, v15
	v_mov_b32_e32 v9, v15
	v_mov_b32_e32 v8, v15
	v_mov_b32_e32 v7, v15
	v_mov_b32_e32 v6, v15
	v_mov_b32_e32 v5, v15
	v_mov_b32_e32 v4, v15
	v_mov_b32_e32 v3, v15
	v_mov_b32_e32 v2, v15
	v_mov_b32_e32 v1, v15
	v_mov_b32_e32 v0, v15
	v_mov_b32_e32 v31, v15
	v_mov_b32_e32 v30, v15
	v_mov_b32_e32 v29, v15
	v_mov_b32_e32 v28, v15
	v_mov_b32_e32 v27, v15
	v_mov_b32_e32 v26, v15
	v_mov_b32_e32 v25, v15
	v_mov_b32_e32 v24, v15
	v_mov_b32_e32 v23, v15
	v_mov_b32_e32 v22, v15
	v_mov_b32_e32 v21, v15
	v_mov_b32_e32 v20, v15
	v_mov_b32_e32 v19, v15
	v_mov_b32_e32 v18, v15
	v_mov_b32_e32 v17, v15
	v_mov_b32_e32 v16, v15
	v_mov_b32_e32 v47, v15
	v_mov_b32_e32 v46, v15
	v_mov_b32_e32 v45, v15
	v_mov_b32_e32 v44, v15
	v_mov_b32_e32 v43, v15
	v_mov_b32_e32 v42, v15
	v_mov_b32_e32 v41, v15
	v_mov_b32_e32 v40, v15
	v_mov_b32_e32 v39, v15
	v_mov_b32_e32 v38, v15
	v_mov_b32_e32 v37, v15
	v_mov_b32_e32 v36, v15
	v_mov_b32_e32 v35, v15
	v_mov_b32_e32 v34, v15
	v_mov_b32_e32 v33, v15
	v_mov_b32_e32 v32, v15
	v_mov_b32_e32 v63, v15
	v_mov_b32_e32 v62, v15
	v_mov_b32_e32 v61, v15
	v_mov_b32_e32 v60, v15
	v_mov_b32_e32 v59, v15
	v_mov_b32_e32 v58, v15
	v_mov_b32_e32 v57, v15
	v_mov_b32_e32 v56, v15
	v_mov_b32_e32 v55, v15
	v_mov_b32_e32 v54, v15
	v_mov_b32_e32 v53, v15
	v_mov_b32_e32 v52, v15
	v_mov_b32_e32 v51, v15
	v_mov_b32_e32 v50, v15
	v_mov_b32_e32 v49, v15
	v_mov_b32_e32 v48, v15
	s_cbranch_vccnz .LBB0_368
	v_cvt_pk_bf16_f32 v4, v98, 0
	v_cndmask_b32_e64 v1, v175, v176, s[40:41]
	v_lshlrev_b32_e32 v4, 16, v4
	v_cndmask_b32_e64 v1, v1, 0, s[62:63]
	v_sub_f32_e32 v4, v98, v4
	v_cvt_pk_bf16_f32 v5, v4, 0
	v_cndmask_b32_e64 v128, 0, v1, s[38:39]
	v_cvt_pk_bf16_f32 v1, v99, 0
	v_cndmask_b32_e64 v2, v177, v178, s[40:41]
	v_lshlrev_b32_e32 v5, 16, v5
	v_lshlrev_b32_e32 v1, 16, v1
	v_cndmask_b32_e64 v2, v2, 0, s[62:63]
	v_sub_f32_e32 v5, v4, v5
	v_cvt_pk_bf16_f32 v4, v98, v4
	v_sub_f32_e32 v1, v99, v1
	v_cndmask_b32_e64 v126, v2, v4, s[38:39]
	v_cvt_pk_bf16_f32 v4, v1, 0
	v_cndmask_b32_e64 v0, v173, -v173, s[40:41]
	v_lshlrev_b32_e32 v4, 16, v4
	v_cndmask_b32_e64 v0, v0, 0, s[62:63]
	v_cndmask_b32_e64 v3, v179, v180, s[40:41]
	v_sub_f32_e32 v4, v1, v4
	v_cndmask_b32_e64 v3, v3, 0, s[62:63]
	v_cvt_pk_bf16_f32 v5, v5, v0
	v_cvt_pk_bf16_f32 v0, v4, v0
	s_or_b32 s21, s21, 64
	v_cndmask_b32_e64 v139, v3, v0, s[38:39]
	v_cvt_f32_u32_e32 v0, s21
	v_cvt_pk_bf16_f32 v1, v99, v1
	v_cndmask_b32_e64 v138, v2, v1, s[38:39]
	s_sub_i32 s20, 64, s14
	v_lshrrev_b32_e32 v1, 16, v0
	v_and_b32_e32 v0, 0x7fff0000, v0
	v_or_b32_e32 v0, v1, v0
	v_cndmask_b32_e64 v127, v3, v5, s[38:39]
	v_cndmask_b32_e64 v130, v0, v96, s[38:39]
	s_sub_i32 s27, s15, s23
	v_xor_b32_e32 v154, 0x80000000, v92
	v_mov_b32_e32 v0, 0
	v_mov_b64_e32 v[144:145], v[128:129]
	s_sub_i32 s19, 64, s23
	v_mov_b32_e32 v140, v128
	v_mov_b32_e32 v141, v129
	v_cndmask_b32_e64 v131, v1, v95, s[38:39]
	v_mov_b32_e32 v133, v129
	v_cndmask_b32_e64 v135, v1, v94, s[38:39]
	v_mov_b32_e32 v134, v130
	v_mov_b32_e32 v137, v129
	s_add_i32 s21, s22, s15
	s_add_i32 s22, s27, 63
	s_sub_i32 s23, 63, s14
	s_max_i32 s26, s20, 2
	v_mov_b32_e32 v156, v154
	v_mov_b32_e32 v157, v154
	s_add_i32 s27, s27, 62
	s_mov_b32 s28, 1
	s_mov_b32 s29, 0x8000
	v_mov_b64_e32 v[142:143], v[126:127]
	v_mov_b32_e32 v1, v0
	v_mov_b32_e32 v2, v0
	v_mov_b32_e32 v3, v0
	v_mov_b32_e32 v4, v0
	v_mov_b32_e32 v5, v0
	v_mov_b32_e32 v6, v0
	v_mov_b32_e32 v7, v0
	v_mov_b32_e32 v8, v0
	v_mov_b32_e32 v9, v0
	v_mov_b32_e32 v10, v0
	v_mov_b32_e32 v11, v0
	v_mov_b32_e32 v12, v0
	v_mov_b32_e32 v13, v0
	v_mov_b32_e32 v14, v0
	v_mov_b32_e32 v15, v0
	v_mov_b32_e32 v16, v0
	v_mov_b32_e32 v17, v0
	v_mov_b32_e32 v18, v0
	v_mov_b32_e32 v19, v0
	v_mov_b32_e32 v20, v0
	v_mov_b32_e32 v21, v0
	v_mov_b32_e32 v22, v0
	v_mov_b32_e32 v23, v0
	v_mov_b32_e32 v24, v0
	v_mov_b32_e32 v25, v0
	v_mov_b32_e32 v26, v0
	v_mov_b32_e32 v27, v0
	v_mov_b32_e32 v28, v0
	v_mov_b32_e32 v29, v0
	v_mov_b32_e32 v30, v0
	v_mov_b32_e32 v31, v0
	v_mov_b32_e32 v32, v0
	v_mov_b32_e32 v33, v0
	v_mov_b32_e32 v34, v0
	v_mov_b32_e32 v35, v0
	v_mov_b32_e32 v36, v0
	v_mov_b32_e32 v37, v0
	v_mov_b32_e32 v38, v0
	v_mov_b32_e32 v39, v0
	v_mov_b32_e32 v40, v0
	v_mov_b32_e32 v41, v0
	v_mov_b32_e32 v42, v0
	v_mov_b32_e32 v43, v0
	v_mov_b32_e32 v44, v0
	v_mov_b32_e32 v45, v0
	v_mov_b32_e32 v46, v0
	v_mov_b32_e32 v47, v0
	v_mov_b32_e32 v48, v0
	v_mov_b32_e32 v49, v0
	v_mov_b32_e32 v50, v0
	v_mov_b32_e32 v51, v0
	v_mov_b32_e32 v52, v0
	v_mov_b32_e32 v53, v0
	v_mov_b32_e32 v54, v0
	v_mov_b32_e32 v55, v0
	v_mov_b32_e32 v56, v0
	v_mov_b32_e32 v57, v0
	v_mov_b32_e32 v58, v0
	v_mov_b32_e32 v59, v0
	v_mov_b32_e32 v60, v0
	v_mov_b32_e32 v61, v0
	v_mov_b32_e32 v62, v0
	v_mov_b32_e32 v63, v0
	v_readfirstlane_b32 s100, v148
	v_readfirstlane_b32 s101, v149
	s_nop 1
	v_subrev_u32_e32 v146, s100, v146
	v_subrev_u32_e32 v148, s100, v148
	v_mov_b32_e32 v112, v191
	v_add_u32_e32 v197, 0x2000, v181
	v_add_u32_e32 v196, v197, v183
	s_cmpk_lt_u32 s17, 0x100
	s_cbranch_scc1 .Latt_sp
	s_setprio 1
; #define ATT_DIAG_BIAS(s0, s1) do { const float dqh_ = dq - (float)(4 * hi); _Pragma("unroll") for (int r = 0; r < 16; ++r) { const float c_ = (float)((r & 3) + 8 * (r >> 2)); \
;         s0[r] = __builtin_fmaf(-sl, __builtin_fabsf(dqh_ - c_), s0[r]); s1[r] = __builtin_fmaf(-sl, __builtin_fabsf(dqh_ - (c_ + 32.f)), s1[r]); } } while (0)
;     ...
;         { const bool diag = tau == td; const float dq = (float)(tq - tau * KVBLK);
;           if (ABL & 2) { asm volatile("" : "=v"(pa0), "=v"(pa1), "=v"(pa2), "=v"(pa3), "=v"(pb0), "=v"(pb1), "=v"(pb2), "=v"(pb3) : "v"(sa0), "v"(sa1), "v"(sb0), "v"(sb1)); } else {
;           if (diag) { ATT_DIAG_BIAS(sa0, sa1); ATT_DIAG_BIAS(sb0, sb1); }
.Latt_sp:
	s_branch .LBB0_339
.Latt_diag:
	s_lshl_b32 s34, s30, 6
	v_subrev_u32_e32 v128, s34, v171
	v_cvt_f32_i32_e32 v199, v128
	s_mov_b32 s34, 0xc2000000
	v_sub_f32_e32 v128, v199, v184
	s_mov_b32 s35, 0xc2040000
	v_pk_add_f32 v[158:159], v[128:129], s[34:35] op_sel_hi:[0,1]
	s_mov_b32 s34, -2.0
	s_mov_b32 s35, 0xc0400000
	v_pk_add_f32 v[160:161], v[128:129], s[34:35] op_sel_hi:[0,1]
	s_mov_b32 s34, 0xc2080000
	s_mov_b32 s35, 0xc20c0000
	v_pk_add_f32 v[162:163], v[128:129], s[34:35] op_sel_hi:[0,1]
	s_mov_b32 s34, 0xc1000000
	s_mov_b32 s35, 0xc1100000
	v_pk_add_f32 v[186:187], v[128:129], s[34:35] op_sel_hi:[0,1]
	s_mov_b32 s34, 0xc2200000
	s_mov_b32 s35, 0xc2240000
	v_pk_add_f32 v[188:189], v[128:129], s[34:35] op_sel_hi:[0,1]
	s_mov_b32 s34, 0xc1200000
	s_mov_b32 s35, 0xc1300000
	v_pk_add_f32 v[192:193], v[128:129], s[34:35] op_sel_hi:[0,1]
	s_mov_b32 s34, 0xc2280000
	s_mov_b32 s35, 0xc22c0000
	v_pk_add_f32 v[194:195], v[128:129], s[34:35] op_sel_hi:[0,1]
	s_mov_b32 s34, 0xc1800000
	s_mov_b32 s35, 0xc1880000
	v_pk_add_f32 v[200:201], v[128:129], s[34:35] op_sel_hi:[0,1]
	s_mov_b32 s34, 0xc2400000
	s_mov_b32 s35, 0xc2440000
	v_pk_add_f32 v[202:203], v[128:129], s[34:35] op_sel_hi:[0,1]
	s_mov_b32 s34, 0xc1900000
	s_mov_b32 s35, 0xc1980000
	v_pk_add_f32 v[204:205], v[128:129], s[34:35] op_sel_hi:[0,1]
	s_mov_b32 s34, 0xc2480000
	s_mov_b32 s35, 0xc24c0000
	v_pk_add_f32 v[206:207], v[128:129], s[34:35] op_sel_hi:[0,1]
	s_mov_b32 s34, 0xc1c00000
	s_mov_b32 s35, 0xc1c80000
	v_pk_add_f32 v[208:209], v[128:129], s[34:35] op_sel_hi:[0,1]
	s_mov_b32 s34, 0xc2600000
	s_mov_b32 s35, 0xc2640000
	v_pk_add_f32 v[210:211], v[128:129], s[34:35] op_sel_hi:[0,1]
	s_mov_b32 s34, 0xc1d00000
	s_mov_b32 s35, 0xc1d80000
	v_pk_add_f32 v[214:215], v[128:129], s[34:35] op_sel_hi:[0,1]
	s_mov_b32 s34, 0xc2680000
	s_mov_b32 s35, 0xc26c0000
	v_add_f32_e32 v155, -1.0, v128
	v_pk_add_f32 v[222:223], v[128:129], s[34:35] op_sel_hi:[0,1]
	v_and_b32_e32 v159, 0x7fffffff, v159
	v_and_b32_e32 v158, 0x7fffffff, v158
	v_and_b32_e32 v163, 0x7fffffff, v163
	v_and_b32_e32 v162, 0x7fffffff, v162
	v_and_b32_e32 v187, 0x7fffffff, v187
	v_and_b32_e32 v186, 0x7fffffff, v186
	v_and_b32_e32 v189, 0x7fffffff, v189
	v_and_b32_e32 v188, 0x7fffffff, v188
	v_and_b32_e32 v193, 0x7fffffff, v193
	v_and_b32_e32 v192, 0x7fffffff, v192
	v_and_b32_e32 v195, 0x7fffffff, v195
	v_and_b32_e32 v194, 0x7fffffff, v194
	v_and_b32_e32 v201, 0x7fffffff, v201
	v_and_b32_e32 v200, 0x7fffffff, v200
	v_and_b32_e32 v203, 0x7fffffff, v203
	v_and_b32_e32 v202, 0x7fffffff, v202
	v_and_b32_e32 v205, 0x7fffffff, v205
	v_and_b32_e32 v204, 0x7fffffff, v204
	v_and_b32_e32 v207, 0x7fffffff, v207
	v_and_b32_e32 v206, 0x7fffffff, v206
	v_and_b32_e32 v209, 0x7fffffff, v209
	v_and_b32_e32 v208, 0x7fffffff, v208
	v_and_b32_e32 v211, 0x7fffffff, v211
	v_and_b32_e32 v210, 0x7fffffff, v210
	v_and_b32_e32 v215, 0x7fffffff, v215
	v_and_b32_e32 v214, 0x7fffffff, v214
	v_and_b32_e32 v223, 0x7fffffff, v223
	v_and_b32_e32 v222, 0x7fffffff, v222
	v_and_b32_e32 v161, 0x7fffffff, v161
	v_and_b32_e32 v160, 0x7fffffff, v160
	v_and_b32_e32 v228, 0x7fffffff, v128
	v_and_b32_e32 v229, 0x7fffffff, v155
	v_mov_b32_e32 v155, v154
	v_pk_fma_f32 v[94:95], v[154:155], v[214:215], v[94:95]
	v_pk_fma_f32 v[92:93], v[154:155], v[208:209], v[92:93]
	v_pk_fma_f32 v[90:91], v[154:155], v[204:205], v[90:91]
	v_pk_fma_f32 v[88:89], v[154:155], v[200:201], v[88:89]
	v_pk_fma_f32 v[86:87], v[154:155], v[192:193], v[86:87]
	v_pk_fma_f32 v[84:85], v[154:155], v[186:187], v[84:85]
	v_pk_fma_f32 v[82:83], v[154:155], v[160:161], v[82:83]
	v_pk_fma_f32 v[80:81], v[156:157], v[228:229], v[80:81]
	v_pk_fma_f32 v[78:79], v[154:155], v[222:223], v[78:79]
	v_pk_fma_f32 v[76:77], v[154:155], v[210:211], v[76:77]
	v_pk_fma_f32 v[74:75], v[154:155], v[206:207], v[74:75]
	v_pk_fma_f32 v[72:73], v[154:155], v[202:203], v[72:73]
	v_pk_fma_f32 v[70:71], v[154:155], v[194:195], v[70:71]
	v_pk_fma_f32 v[68:69], v[154:155], v[188:189], v[68:69]
	v_pk_fma_f32 v[66:67], v[154:155], v[162:163], v[66:67]
	v_pk_fma_f32 v[64:65], v[156:157], v[158:159], v[64:65]
	v_pk_fma_f32 v[126:127], v[154:155], v[214:215], v[126:127]
	v_pk_fma_f32 v[124:125], v[154:155], v[208:209], v[124:125]
	v_pk_fma_f32 v[122:123], v[154:155], v[204:205], v[122:123]
	v_pk_fma_f32 v[120:121], v[154:155], v[200:201], v[120:121]
	v_pk_fma_f32 v[118:119], v[154:155], v[192:193], v[118:119]
	v_pk_fma_f32 v[116:117], v[154:155], v[186:187], v[116:117]
	v_pk_fma_f32 v[114:115], v[154:155], v[160:161], v[114:115]
	v_pk_fma_f32 v[112:113], v[156:157], v[228:229], v[112:113]
	v_pk_fma_f32 v[110:111], v[154:155], v[222:223], v[110:111]
	v_pk_fma_f32 v[108:109], v[154:155], v[210:211], v[108:109]
	v_pk_fma_f32 v[106:107], v[154:155], v[206:207], v[106:107]
	v_pk_fma_f32 v[104:105], v[154:155], v[202:203], v[104:105]
	v_pk_fma_f32 v[102:103], v[154:155], v[194:195], v[102:103]
	v_pk_fma_f32 v[100:101], v[154:155], v[188:189], v[100:101]
	v_pk_fma_f32 v[98:99], v[154:155], v[162:163], v[98:99]
	v_pk_fma_f32 v[96:97], v[156:157], v[158:159], v[96:97]
	s_branch .LBB0_341

; #define ATT_DMA(i, slot) do { if (ABL & 1) break; const long off_ = (long)ATT_TAU(i) * KVBLK * INW; \
;         glds16(ksrc + off_, (unsigned)__builtin_amdgcn_readfirstlane(kdst + (slot) * SLOTB)); glds16(vsrc + off_, (unsigned)__builtin_amdgcn_readfirstlane(vdst + (slot) * SLOTB)); } while (0)
; #define ATT_BARV(N) do { if (ABL & 16) asm volatile("s_waitcnt vmcnt(" #N ") lgkmcnt(0)\n\ts_nop 11" ::: "memory"); else asm volatile("s_waitcnt vmcnt(" #N ") lgkmcnt(0)\n\ts_barrier\n\ts_nop 11" ::: "memory"); } while (0)
; #define ATT_BAR() do { if (ABL & 16) asm volatile("s_waitcnt lgkmcnt(0)" ::: "memory"); else asm volatile("s_waitcnt lgkmcnt(0)\n\ts_barrier" ::: "memory"); } while (0)
; #define ATT_SB() __builtin_amdgcn_sched_barrier(0)
; #define ATT_LDQ() const bf16x8 qf0 = *(const __attribute__((address_space(3))) bf16x8*)(qp), qf1 = *(const __attribute__((address_space(3))) bf16x8*)(qp + 1024), qf2 = *(const __attribute__((address_space(3))) bf16x8*)(qp + 2048), qf3 = *(const __attribute__((address_space(3))) bf16x8*)(qp + 3072)
; #define ATT_KA(off) (*(const __attribute__((address_space(3))) bf16x8*)(kp + (off)))
;     ...
;     for (int i = 1; i < NTe; ++i) {
;         const int tau = ATT_TAU(i), slot = i & 3;
;         { const int id_ = i + 2 < NTe ? i + 2 : NTe - 1; ATT_DMA(id_, (i + 2) & 3); }
;         { const lds_cptr vp = vp0 + ((i - 1) & 3) * SLOTB, kp = kp0 + slot * SLOTB;
;           ATT_VFR(a, 0); ATT_VFR(b, 1);
;           const bf16x8 ka0 = ATT_KA(0), ka1 = ATT_KA(2048), ka2 = ATT_KB(0), ka3 = ATT_KB(2048);
;           ATT_SB();
;           ATT_PVK(a, pa0, pb0); ATT_SB();
;           ATT_VFR(c, 2); ATT_SB();
;           ATT_PVK(b, pa1, pb1); ATT_SB();
;           ATT_VFR(d, 3);
;           const bf16x8 kb0 = ATT_KA(4096), kb1 = ATT_KA(6144), kb2 = ATT_KB(4096), kb3 = ATT_KB(6144);
;           ATT_LDQ();
;           ATT_SB();
;           ATT_PVK(c, pa2, pb2); ATT_SB();
;           ATT_PVK(d, pa3, pb3); ATT_SB();
;           ATT_QKA(); ATT_QKB(); }
;         ATT_SB();
;         ATT_BARV(2);
;         __builtin_amdgcn_s_setprio(1);
;         ATT_SB();
;     ...
;           { const int in_ = i + 1 < NTe ? i + 1 : i; const int tn_ = ATT_TAU(in_); const int sdn_ = ATT_SIDE(tn_);
;             if (redo || sdn_ != ATT_SIDE(tau)) { ATT_QAUG(sdn_); }
;             ATT_KAUG(tn_); } } }
;         __builtin_amdgcn_s_setprio(0);
;         ATT_SB(); ATT_BAR(); ATT_SB();
.LBB0_338:
	v_cvt_pk_bf16_f32 v103, v86, v87
	v_cvt_pk_bf16_f32 v86, v92, v93
	v_add_f32_e32 v153, v153, v79
	v_cvt_pk_bf16_f32 v100, v80, v81
	v_cvt_pk_bf16_f32 v101, v82, v83
	v_cvt_pk_bf16_f32 v102, v84, v85
	v_cvt_pk_bf16_f32 v84, v88, v97
	v_cvt_pk_bf16_f32 v85, v90, v99
	v_cvt_pk_bf16_f32 v87, v94, v73
	v_cvt_pk_bf16_f32 v80, v64, v65
	v_cvt_pk_bf16_f32 v81, v66, v67
	v_cvt_pk_bf16_f32 v82, v68, v69
	v_cvt_pk_bf16_f32 v83, v70, v71
	v_cvt_pk_bf16_f32 v64, v72, v89
	v_cvt_pk_bf16_f32 v65, v74, v91
	v_cvt_pk_bf16_f32 v66, v76, v77
	v_cvt_pk_bf16_f32 v67, v78, v75
	v_cvt_pk_bf16_f32 v88, v193, v158
	v_cvt_pk_bf16_f32 v89, v194, v112
	v_cvt_pk_bf16_f32 v90, v195, v114
	v_cvt_pk_bf16_f32 v91, v198, v160
	v_cvt_pk_bf16_f32 v76, v161, v162
	v_cvt_pk_bf16_f32 v77, v163, v120
	v_cvt_pk_bf16_f32 v78, v121, v122
	v_cvt_pk_bf16_f32 v79, v123, v124
	v_cvt_pk_bf16_f32 v72, v192, v128
	v_cvt_pk_bf16_f32 v73, v159, v96
	v_cvt_pk_bf16_f32 v74, v113, v98
	v_cvt_pk_bf16_f32 v75, v115, v116
	v_cvt_pk_bf16_f32 v68, v117, v118
	v_cvt_pk_bf16_f32 v69, v119, v104
	v_cvt_pk_bf16_f32 v70, v105, v106
	v_cvt_pk_bf16_f32 v71, v107, v108
	v_add_f32_e32 v152, v152, v109
	s_and_b32 vcc_lo, s29, 0x6000
	s_add_i32 vcc_hi, s29, 0x2000
	s_and_b32 vcc_hi, vcc_hi, 0x6000
	v_add_u32_e32 v112, vcc_lo, v191
	v_add_u32_e32 v197, vcc_hi, v181
	v_add_u32_e32 v196, v197, v183
	s_mul_i32 vcc_lo, s98, 0x10001
	s_mov_b32 exec_lo, 0
	v_mov_b32_e32 v130, vcc_lo
	v_mov_b32_e32 v131, s98
	v_mov_b32_e32 v134, vcc_lo
	v_mov_b32_e32 v135, s98
	s_mov_b32 exec_lo, -1
	s_waitcnt lgkmcnt(0)
	s_barrier
	s_cmp_eq_u32 s28, s26
	s_cbranch_scc1 .LBB0_367
.LBB0_339:
	ds_read_b64_tr_b16 v[92:93], v112 offset:32768
	ds_read_b64_tr_b16 v[94:95], v112 offset:33280
	ds_read_b64_tr_b16 v[96:97], v112 offset:33792
	ds_read_b64_tr_b16 v[98:99], v112 offset:34304
	ds_read_b64_tr_b16 v[104:105], v112 offset:36864
	ds_read_b64_tr_b16 v[106:107], v112 offset:37376
	ds_read_b64_tr_b16 v[108:109], v112 offset:37888
	ds_read_b64_tr_b16 v[110:111], v112 offset:38400
	ds_read_b128 v[158:161], v197
	ds_read_b128 v[192:195], v197 offset:2048
	ds_read_b128 v[198:201], v196
	ds_read_b128 v[202:205], v196 offset:2048
	s_add_i32 s30, s15, s28
	s_cmp_lt_i32 s28, s19
	s_cselect_b32 s30, s30, s27
	s_add_i32 s36, s28, 2
	s_cmp_lt_i32 s36, s20
	s_cselect_b32 s34, s36, s23
	s_add_i32 s35, s34, s15
	s_sub_i32 s36, s22, s34
	s_cmp_lt_i32 s34, s19
	s_cselect_b32 s36, s35, s36
	s_waitcnt lgkmcnt(10)
	v_mfma_f32_32x32x16_bf16 v[48:63], v[88:91], v[92:95], v[48:63]
	s_mul_i32 s34, s36, 0x50000
	s_add_u32 s34, s100, s34
	s_addc_u32 s35, s101, 0
	s_add_i32 s37, s29, 0xffffe000
	s_and_b32 s37, s37, 0x6000
	s_waitcnt lgkmcnt(6)
	v_mfma_f32_32x32x16_bf16 v[32:47], v[88:91], v[104:107], v[32:47]
	s_add_i32 s31, s28, 1
	s_cmp_lt_i32 s31, s20
	s_cselect_b32 s31, s31, s28
	s_add_i32 s98, s31, s15
	v_mfma_f32_32x32x16_bf16 v[16:31], v[100:103], v[92:95], v[16:31]
	s_sub_i32 s99, s22, s31
	s_cmp_lt_i32 s31, s19
	s_cselect_b32 s31, s98, s99
	v_mfma_f32_32x32x16_bf16 v[0:15], v[100:103], v[104:107], v[0:15]
	ds_read_b64_tr_b16 v[88:89], v112 offset:34816
	ds_read_b64_tr_b16 v[90:91], v112 offset:35328
	ds_read_b64_tr_b16 v[92:93], v112 offset:38912
	ds_read_b64_tr_b16 v[94:95], v112 offset:39424
	v_mfma_f32_32x32x16_bf16 v[48:63], v[76:79], v[96:99], v[48:63]
	s_add_i32 m0, s37, s45
	s_nop 0
	global_load_lds_dwordx4 v148, s[34:35]
	s_add_i32 m0, s37, s18
	s_nop 0
	global_load_lds_dwordx4 v146, s[34:35]
	s_waitcnt lgkmcnt(8)
	v_mfma_f32_32x32x16_bf16 v[32:47], v[76:79], v[108:111], v[32:47]
	s_sub_i32 s98, s30, s21
	s_sub_i32 s99, s31, s21
	s_mul_i32 s99, s98, s99
	s_addk_i32 s29, 0x2000
	s_add_i32 s27, s27, -1
	v_mfma_f32_32x32x16_bf16 v[16:31], v[84:87], v[96:99], v[16:31]
	s_add_i32 s28, s28, 1
	s_flbit_i32_b32 s34, s31
	s_sub_i32 s35, s34, 24
	s_lshl_b32 s35, s31, s35
	s_sub_i32 s34, 0xa3, s34
	v_mfma_f32_32x32x16_bf16 v[0:15], v[84:87], v[108:111], v[0:15]
	ds_read_b64_tr_b16 v[76:77], v112 offset:35840
	ds_read_b64_tr_b16 v[78:79], v112 offset:36352
	ds_read_b64_tr_b16 v[84:85], v112 offset:39936
	ds_read_b64_tr_b16 v[86:87], v112 offset:40448
	ds_read_b128 v[206:209], v197 offset:4096
	ds_read_b128 v[228:231], v197 offset:6144
	ds_read_b128 v[232:235], v196 offset:4096
	ds_read_b128 v[236:239], v196 offset:6144
	ds_read_b128 v[240:243], v174
	ds_read_b128 v[244:247], v174 offset:1024
	ds_read_b128 v[248:251], v174 offset:2048
	ds_read_b128 v[186:189], v174 offset:3072
	s_waitcnt lgkmcnt(14)
	v_mfma_f32_32x32x16_bf16 v[48:63], v[72:75], v[88:91], v[48:63]
	s_waitcnt lgkmcnt(12)
	v_mfma_f32_32x32x16_bf16 v[32:47], v[72:75], v[92:95], v[32:47]
	s_lshl_b32 s34, s34, 7
	s_add_i32 s34, s34, s35
	s_cmp_eq_u32 s31, 0
	s_cselect_b32 s98, 0, s34
	v_mfma_f32_32x32x16_bf16 v[16:31], v[80:83], v[88:91], v[16:31]
	v_mfma_f32_32x32x16_bf16 v[0:15], v[80:83], v[92:95], v[0:15]
	s_waitcnt lgkmcnt(10)
	v_mfma_f32_32x32x16_bf16 v[48:63], v[68:71], v[76:79], v[48:63]
	s_waitcnt lgkmcnt(8)
	v_mfma_f32_32x32x16_bf16 v[32:47], v[68:71], v[84:87], v[32:47]
	v_mfma_f32_32x32x16_bf16 v[16:31], v[64:67], v[76:79], v[16:31]
	v_mfma_f32_32x32x16_bf16 v[0:15], v[64:67], v[84:87], v[0:15]
	v_mfma_f32_32x32x16_bf16 v[112:127], v[134:137], v[142:145], 0
	v_mfma_f32_32x32x16_bf16 v[96:111], v[130:133], v[142:145], 0
	v_mfma_f32_32x32x16_bf16 v[80:95], v[134:137], v[138:141], 0
	v_mfma_f32_32x32x16_bf16 v[64:79], v[130:133], v[138:141], 0
	s_waitcnt lgkmcnt(3)
	v_mfma_f32_32x32x16_bf16 v[112:127], v[158:161], v[240:243], v[112:127]
	v_mfma_f32_32x32x16_bf16 v[96:111], v[192:195], v[240:243], v[96:111]
	s_waitcnt lgkmcnt(1)
	v_mfma_f32_32x32x16_bf16 v[80:95], v[206:209], v[248:251], v[80:95]
	v_mfma_f32_32x32x16_bf16 v[64:79], v[228:231], v[248:251], v[64:79]
	v_mfma_f32_32x32x16_bf16 v[112:127], v[198:201], v[244:247], v[112:127]
	v_mfma_f32_32x32x16_bf16 v[96:111], v[202:205], v[244:247], v[96:111]
	s_waitcnt lgkmcnt(0)
	v_mfma_f32_32x32x16_bf16 v[80:95], v[232:235], v[186:189], v[80:95]
	v_mfma_f32_32x32x16_bf16 v[64:79], v[236:239], v[186:189], v[64:79]
	s_cmp_eq_u32 s30, s21
	s_cselect_b64 s[42:43], -1, 0
	s_cmp_lg_u32 s30, s21
	s_waitcnt vmcnt(2) lgkmcnt(0)
	s_barrier
	s_nop 1
	s_cbranch_scc0 .Latt_diag

; #define ATT_VFR(n, ks) const s16x4 l0##n = vtr(vp + (ks) * 1024), h0##n = vtr(vp + (ks) * 1024 + 512), l1##n = vtr(vp + 4096 + (ks) * 1024), h1##n = vtr(vp + 4096 + (ks) * 1024 + 512)
;     ...
;     { const lds_cptr vp = vp0 + ((NTe - 1) & 3) * SLOTB;
;       ATT_VFR(a, 0); ATT_VFR(b, 1); ATT_VFR(c, 2); ATT_VFR(d, 3);
;       ATT_PVK(a, pa0, pb0); ATT_PVK(b, pa1, pb1); ATT_PVK(c, pa2, pb2); ATT_PVK(d, pa3, pb3); }
.LBB0_367:
	s_setprio 0
	v_readlane_b32 s27, v255, 15
	s_mov_b32 s28, 0xed001000
